# v84 + mLSTM scan S3 k-loop: all six LDS fragment reads issued at the top of each iteration
# speedup vs baseline: 1.0119x; 1.0021x over previous
.LBB0_227:
	v_add_u32_e32 v89, s86, v214
	v_add_u32_e32 v94, s86, v212
	ds_read_b128 v[90:93], v89 offset:34816
	v_add_u32_e32 v95, 0x19800, v94
	v_add_u32_e32 v98, 0x1a900, v94
	ds_read_b128 v[94:97], v95
	ds_read_b128 v[98:101], v98
	ds_read_b128 v[246:249], v89 offset:39168
	v_add_u32_e32 v102, 0x11000, v89
	v_add_u32_e32 v245, 0x12100, v89
	ds_read_b128 v[250:253], v102
	ds_read_b128 v[102:105], v245
	s_add_i32 s86, s86, 64
	s_cmpk_eq_i32 s86, 0x100
	s_waitcnt lgkmcnt(4)
	v_mfma_f32_16x16x32_bf16 v[84:87], v[90:93], v[94:97], v[84:87]
	s_waitcnt lgkmcnt(3)
	v_mfma_f32_16x16x32_bf16 v[80:83], v[90:93], v[98:101], v[80:83]
	s_waitcnt lgkmcnt(2)
	v_mfma_f32_16x16x32_bf16 v[76:79], v[246:249], v[94:97], v[76:79]
	v_mfma_f32_16x16x32_bf16 v[72:75], v[246:249], v[98:101], v[72:75]
	s_waitcnt lgkmcnt(1)
	v_mfma_f32_16x16x32_bf16 v[56:59], v[250:253], v[94:97], v[56:59]
	v_mfma_f32_16x16x32_bf16 v[60:63], v[250:253], v[98:101], v[60:63]
	s_waitcnt lgkmcnt(0)
	v_mfma_f32_16x16x32_bf16 v[64:67], v[102:105], v[94:97], v[64:67]
	v_mfma_f32_16x16x32_bf16 v[68:71], v[102:105], v[98:101], v[68:71]
	s_cbranch_scc0 .LBB0_227
	ds_read_b128 v[90:93], v216
	ds_read_b128 v[94:97], v216 offset:16
	ds_read_b128 v[98:101], v216 offset:32
	ds_read_b128 v[102:105], v216 offset:48
	s_lshl_b32 s84, s84, 7
	s_sub_i32 s90, s94, s84
	s_and_b64 s[86:87], s[2:3], exec
	s_waitcnt lgkmcnt(3)
	v_lshlrev_b32_e32 v89, 16, v90
	v_and_b32_e32 v90, 0xffff0000, v90
	v_add_f32_e32 v89, v89, v90
	v_lshlrev_b32_e32 v90, 16, v91
	v_and_b32_e32 v91, 0xffff0000, v91
	v_add_f32_e32 v90, v90, v91
	v_add_f32_e32 v89, v89, v90
	v_lshlrev_b32_e32 v90, 16, v92
	v_and_b32_e32 v91, 0xffff0000, v92
	v_add_f32_e32 v90, v90, v91
	v_add_f32_e32 v89, v90, v89
	v_lshlrev_b32_e32 v90, 16, v93
	v_and_b32_e32 v91, 0xffff0000, v93
	v_add_f32_e32 v90, v90, v91
	v_add_f32_e32 v89, v90, v89
	s_waitcnt lgkmcnt(2)
	v_lshlrev_b32_e32 v90, 16, v94
	v_and_b32_e32 v91, 0xffff0000, v94
	v_add_f32_e32 v90, v90, v91
	v_lshlrev_b32_e32 v91, 16, v95
	v_and_b32_e32 v92, 0xffff0000, v95
	v_add_f32_e32 v91, v91, v92
	v_add_f32_e32 v90, v90, v91
	v_lshlrev_b32_e32 v91, 16, v96
	v_and_b32_e32 v92, 0xffff0000, v96
	v_add_f32_e32 v91, v91, v92
	v_add_f32_e32 v90, v91, v90
	v_lshlrev_b32_e32 v91, 16, v97
	v_and_b32_e32 v92, 0xffff0000, v97
	v_add_f32_e32 v91, v91, v92
	v_add_f32_e32 v89, 0, v89
	v_add_f32_e32 v90, v91, v90
	v_add_f32_e32 v89, v89, v90
	s_waitcnt lgkmcnt(1)
	v_lshlrev_b32_e32 v90, 16, v98
	v_and_b32_e32 v91, 0xffff0000, v98
	v_add_f32_e32 v90, v90, v91
	v_lshlrev_b32_e32 v91, 16, v99
	v_and_b32_e32 v92, 0xffff0000, v99
	v_add_f32_e32 v91, v91, v92
	v_add_f32_e32 v90, v90, v91
	v_lshlrev_b32_e32 v91, 16, v100
	v_and_b32_e32 v92, 0xffff0000, v100
	v_add_f32_e32 v91, v91, v92
	v_add_f32_e32 v90, v91, v90
	v_lshlrev_b32_e32 v91, 16, v101
	v_and_b32_e32 v92, 0xffff0000, v101
	v_add_f32_e32 v91, v91, v92
	v_add_f32_e32 v90, v91, v90
	v_add_f32_e32 v89, v89, v90
	s_waitcnt lgkmcnt(0)
	v_lshlrev_b32_e32 v90, 16, v102
	v_and_b32_e32 v91, 0xffff0000, v102
	v_add_f32_e32 v90, v90, v91
	v_lshlrev_b32_e32 v91, 16, v103
	v_and_b32_e32 v92, 0xffff0000, v103
	v_add_f32_e32 v91, v91, v92
	v_add_f32_e32 v90, v90, v91
	v_lshlrev_b32_e32 v91, 16, v104
	v_and_b32_e32 v92, 0xffff0000, v104
	v_add_f32_e32 v91, v91, v92
	v_add_f32_e32 v90, v91, v90
	v_lshlrev_b32_e32 v91, 16, v105
	v_and_b32_e32 v92, 0xffff0000, v105
	v_add_f32_e32 v91, v91, v92
	s_cselect_b32 s84, s84, s90
	ds_read_b128 v[92:95], v182
	s_add_i32 s84, s84, s89
	v_or_b32_e32 v96, s84, v200
	v_ashrrev_i32_e32 v97, 31, v96
	v_lshlrev_b64 v[96:97], 11, v[96:97]
	v_lshl_add_u64 v[100:101], v[146:147], 0, v[96:97]
	ds_read_b128 v[96:99], v182 offset:64
	s_waitcnt lgkmcnt(1)
	v_mul_f32_e32 v84, v84, v92
	v_mul_f32_e32 v80, v80, v92
	v_cvt_pk_bf16_f32 v84, v84, v84
	global_store_short v[100:101], v84, off
	v_cvt_pk_bf16_f32 v80, v80, v80
	global_store_short v[100:101], v80, off offset:32
	v_or_b32_e32 v100, s84, v201
	v_ashrrev_i32_e32 v101, 31, v100
	v_lshlrev_b64 v[100:101], 11, v[100:101]
	v_mul_f32_e32 v80, v85, v93
	v_lshl_add_u64 v[100:101], v[146:147], 0, v[100:101]
	v_cvt_pk_bf16_f32 v80, v80, v80
	global_store_short v[100:101], v80, off
	v_mul_f32_e32 v80, v81, v93
	v_cvt_pk_bf16_f32 v80, v80, v80
	global_store_short v[100:101], v80, off offset:32
	v_or_b32_e32 v80, s84, v203
	v_ashrrev_i32_e32 v81, 31, v80
	v_lshlrev_b64 v[80:81], 11, v[80:81]
	v_lshl_add_u64 v[80:81], v[146:147], 0, v[80:81]
	v_mul_f32_e32 v84, v86, v94
	v_mul_f32_e32 v82, v82, v94
	v_cvt_pk_bf16_f32 v84, v84, v84
	global_store_short v[80:81], v84, off
	v_cvt_pk_bf16_f32 v82, v82, v82
	global_store_short v[80:81], v82, off offset:32
	v_or_b32_e32 v80, s84, v204
	v_ashrrev_i32_e32 v81, 31, v80
	v_lshlrev_b64 v[80:81], 11, v[80:81]
	v_mul_f32_e32 v82, v87, v95
	v_lshl_add_u64 v[80:81], v[146:147], 0, v[80:81]
	v_cvt_pk_bf16_f32 v82, v82, v82
	global_store_short v[80:81], v82, off
	v_mul_f32_e32 v82, v83, v95
	v_cvt_pk_bf16_f32 v82, v82, v82
	global_store_short v[80:81], v82, off offset:32
	v_or_b32_e32 v80, s84, v205
	v_ashrrev_i32_e32 v81, 31, v80
	v_lshlrev_b64 v[80:81], 11, v[80:81]
	v_lshl_add_u64 v[80:81], v[146:147], 0, v[80:81]
	s_waitcnt lgkmcnt(0)
	v_mul_f32_e32 v76, v76, v96
	v_mul_f32_e32 v72, v72, v96
	v_cvt_pk_bf16_f32 v76, v76, v76
	global_store_short v[80:81], v76, off
	v_cvt_pk_bf16_f32 v72, v72, v72
	global_store_short v[80:81], v72, off offset:32
	v_or_b32_e32 v80, s84, v206
	v_ashrrev_i32_e32 v81, 31, v80
	v_lshlrev_b64 v[80:81], 11, v[80:81]
	v_mul_f32_e32 v72, v77, v97
	v_add_f32_e32 v90, v91, v90
	v_lshl_add_u64 v[80:81], v[146:147], 0, v[80:81]
	v_cvt_pk_bf16_f32 v72, v72, v72
	v_add_f32_e32 v89, v89, v90
	global_store_short v[80:81], v72, off
	v_mul_f32_e32 v72, v73, v97
	s_nop 1
	v_add_f32_dpp v89, v89, v89 quad_perm:[1,0,3,2] row_mask:0xf bank_mask:0xf
	v_cvt_pk_bf16_f32 v72, v72, v72
	global_store_short v[80:81], v72, off offset:32
	v_or_b32_e32 v72, s84, v207
	v_ashrrev_i32_e32 v73, 31, v72
	v_lshlrev_b64 v[72:73], 11, v[72:73]
	v_lshl_add_u64 v[72:73], v[146:147], 0, v[72:73]
	v_mul_f32_e32 v76, v78, v98
	v_mul_f32_e32 v74, v74, v98
	s_waitcnt lgkmcnt(0)
	s_nop 0
	v_cvt_pk_bf16_f32 v76, v76, v76
	global_store_short v[72:73], v76, off
	v_cvt_pk_bf16_f32 v74, v74, v74
	global_store_short v[72:73], v74, off offset:32
	v_or_b32_e32 v72, s84, v208
	v_mov_b32_dpp v90, v89 quad_perm:[2,3,0,1] row_mask:0xf bank_mask:0xf
	v_ashrrev_i32_e32 v73, 31, v72
	v_lshlrev_b64 v[72:73], 11, v[72:73]
	v_mul_f32_e32 v74, v79, v99
	v_lshl_add_u64 v[72:73], v[146:147], 0, v[72:73]
	v_cvt_pk_bf16_f32 v74, v74, v74
	global_store_short v[72:73], v74, off
	v_mul_f32_e32 v74, v75, v99
	v_cvt_pk_bf16_f32 v76, v64, v65
	v_cvt_pk_bf16_f32 v74, v74, v74
	global_store_short v[72:73], v74, off offset:32
	s_waitcnt lgkmcnt(0)
	s_barrier
	v_cvt_pk_bf16_f32 v72, v56, v57
	v_cvt_pk_bf16_f32 v73, v58, v59
	v_cvt_pk_bf16_f32 v77, v66, v67
	ds_write2_b64 v217, v[72:73], v[76:77] offset1:4
	v_add_u32_e32 v76, 0x1000, v217
	v_cvt_pk_bf16_f32 v74, v60, v61
	v_cvt_pk_bf16_f32 v75, v62, v63
	v_cvt_pk_bf16_f32 v72, v68, v69
	v_cvt_pk_bf16_f32 v73, v70, v71
	ds_write2_b64 v76, v[74:75], v[72:73] offset0:32 offset1:36
	s_and_saveexec_b64 s[86:87], s[6:7]
	s_cbranch_execz .LBB0_201
	ds_read_b32 v73, v134
	v_add_f32_e32 v72, v89, v90
	s_waitcnt lgkmcnt(0)
	v_fmac_f32_e32 v72, v88, v73
	ds_write_b32 v134, v72
	s_branch .LBB0_201
